# diff-loop DMA block: last m0 hazard nop filled with address SALU; diff finalize C*r multiplies hoisted above the gate-load wait
# baseline (speedup 1.0000x reference)
; template <bool DIFF>
; __device__ __forceinline__ void attn_item(LAS unsigned char* lds, const bf16_t* Z, bf16_t* MIX, int b, int h, int t, float lam, float shift, const float* gain, int tid, int wid, int lane) {
;     ...
;     lane = lane_id(); asm volatile("" : "+v"(lane)); tid = wid * 64 + lane;
;     const int q16 = lane & 15, quad = lane >> 4;
;     const int row0 = b * SEQ + 128 * t + 16 * wid;
;     const int cq = 2 * t + (wid >> 2), nkt = 2 * t + 2;
;     const int qcol = DIFF ? (3072 + 128 * h) : (64 * h);
;     const int kcol = DIFF ? (4096 + 128 * h) : (512 + 64 * h);
;     const int vcol = DIFF ? (5120 + 128 * h) : (1024 + 128 * h);
;     const int gcol = DIFF ? (6144 + 128 * h) : (2048 + 128 * h);
;     const float lg = lg2gamma(h);
;     bf16x8 qf[NC][2];
;     { const bf16_t* qrow = Z + (size_t)(row0 + q16) * DIN + qcol;
; #pragma unroll
;       for (int c = 0; c < NC; ++c)
; #pragma unroll
;           for (int ds = 0; ds < 2; ++ds) qf[c][ds] = __builtin_nontemporal_load((const bf16x8*)(qrow + 64 * c + 32 * ds + 8 * quad)); }
;     f32x4 O[NC][8]; float l[NC];
; #pragma unroll
;     for (int c = 0; c < NC; ++c) { l[c] = 0.f;
; #pragma unroll
;         for (int eb = 0; eb < 8; ++eb) O[c][eb] = (f32x4){0.f, 0.f, 0.f, 0.f}; }
;     const char* kbase = (const char*)(Z + (size_t)(b * SEQ) * DIN + kcol);
;     const char* vbase = (const char*)(Z + (size_t)(b * SEQ) * DIN + vcol);
;     const unsigned krow = (unsigned)(8 * wid + (lane >> 3));
;     const unsigned kso = (krow * DIN + 8u * ((unsigned)(lane & 7) ^ (krow & 7u))) * 2u;
;     const unsigned vrow = (unsigned)(4 * wid + (lane >> 4));
;     const unsigned vso = (vrow * DIN + 8u * (2u * ((((unsigned)lane & 15u) >> 1) ^ (vrow & 7u)) + ((unsigned)lane & 1u))) * 2u;
;     constexpr int ATT_RING = 32768;
;     ...
;     asm volatile("s_waitcnt lgkmcnt(0)\n\ts_barrier" ::: "memory");
;     ATT_DMA(0, 0); ATT_DMA(1, 1);
;     ATT_WAITBAR_ONE();
;     const unsigned kfo = (unsigned)(q16 * 128), ksw = (unsigned)(q16 & 7);
;     const unsigned vrr = (unsigned)(4 * quad + (q16 >> 2)), vx32 = (vrr & 7u) * 32u, vb0 = 16384u + vrr * 256u + 8u * (unsigned)(q16 & 3);
;     const float iq = (float)(128 * t + 16 * wid + q16);
;     int bcur = 0;
;     for (int kt = 0; kt < nkt; ++kt) {
;         const int bnx = (bcur == 2) ? 0 : bcur + 1, bn2 = (bnx == 2) ? 0 : bnx + 1;
;         const bool more2 = (kt + 2 < nkt);
.LBB0_565:
	v_writelane_b32 v254, s2, 51
	s_and_b32 s0, s2, 0xfffff800
	s_mul_hi_i32 s6, s0, 0x3800
	s_mul_i32 s7, s0, 0x3800
	v_readlane_b32 s0, v254, 25
	s_add_u32 s0, s0, s7
	v_readlane_b32 s1, v254, 26
	s_addc_u32 s1, s1, s6
	s_bfe_u32 s9, s95, 0x30003
	s_lshl_b32 s26, s9, 8
	s_add_u32 s76, s0, s26
	s_addc_u32 s77, s1, 0
	s_and_b32 s10, s95, 7
	s_lshl_b32 s0, s10, 2
	s_lshr_b32 s0, s99, s0
	s_and_b32 s0, s0, 15
	s_lshl_b32 s1, s95, 5
	s_and_b32 s11, s1, 0xfffff800
	s_lshl_b32 s8, s0, 7
	v_mov_b32_e32 v8, v183
	s_or_b32 s1, s8, s11
	s_add_i32 s45, s1, s29
	v_and_b32_e32 v9, 15, v8
	v_or_b32_e32 v124, s45, v9
	v_mov_b64_e32 v[4:5], s[30:31]
	v_ashrrev_i32_e32 v10, 4, v8
	s_lshl_b32 s70, s0, 1
	v_mad_i64_i32 v[4:5], s[0:1], v124, s36, v[4:5]
	s_add_i32 s83, s70, s66
	s_lshl_b32 s80, s9, 7
	v_lshl_add_u64 v[126:127], v[4:5], 0, s[26:27]
	v_lshlrev_b32_e32 v4, 3, v10
	s_mul_i32 s1, s11, 0x3800
	v_ashrrev_i32_e32 v5, 31, v4
	s_mul_hi_i32 s0, s11, 0x3800
	s_add_u32 s12, s30, s1
	v_lshl_add_u64 v[4:5], v[4:5], 1, v[126:127]
	s_addc_u32 s13, s31, s0
	v_lshl_add_u64 v[6:7], v[4:5], 0, s[14:15]
	v_add_co_u32_e32 v4, vcc, s16, v4
	s_add_u32 s71, s12, s26
	s_nop 0
	v_addc_co_u32_e32 v5, vcc, 0, v5, vcc
	global_load_dwordx4 v[76:79], v[6:7], off offset:64 nt
	global_load_dwordx4 v[72:75], v[6:7], off offset:128 nt
	global_load_dwordx4 v[80:83], v[4:5], off offset:2048 nt
	global_load_dwordx4 v[68:71], v[6:7], off offset:192 nt
	s_addc_u32 s94, s13, 0
	v_ashrrev_i32_e32 v4, 3, v8
	s_add_u32 s0, s71, 0x2000
	v_add_u32_e32 v5, s34, v4
	v_xor_b32_e32 v4, v4, v8
	s_addc_u32 s1, s94, 0
	v_mul_lo_u32 v5, v5, s37
	v_lshlrev_b32_e32 v4, 3, v4
	s_add_u32 s2, s71, 0x2800
	v_and_or_b32 v4, v4, 56, v5
	v_writelane_b32 v254, s0, 52
	s_addc_u32 s3, s94, 0
	v_lshlrev_b32_e32 v180, 1, v4
	v_add_u32_e32 v4, s35, v10
	v_writelane_b32 v254, s1, 53
	v_lshlrev_b32_e32 v5, 1, v4
	v_writelane_b32 v254, s2, 54
	v_xor_b32_e32 v5, v5, v8
	v_and_b32_e32 v6, 1, v8
	s_waitcnt lgkmcnt(0)
	s_barrier
	v_writelane_b32 v254, s3, 55
	s_add_u32 s4, s2, 0x70000
	s_mov_b32 m0, s90
	v_and_or_b32 v6, v5, 14, v6
	v_mul_lo_u32 v7, v4, s36
	s_addc_u32 s5, s3, 0
	v_lshl_add_u64 v[4:5], s[0:1], 0, v[180:181]
	global_load_lds_dwordx4 v180, s[0:1]
	v_lshl_add_u64 v[4:5], v[4:5], 0, s[96:97]
	s_mov_b32 m0, s17
	v_lshl_or_b32 v132, v6, 4, v7
	global_load_lds_dwordx4 v[4:5], off
	s_mov_b32 m0, s43
	s_add_u32 s0, s71, 0xe2000
	global_load_lds_dwordx4 v132, s[2:3]
	s_mov_b32 m0, s38
	s_addc_u32 s1, s94, 0
	global_load_lds_dwordx4 v132, s[4:5]
	v_writelane_b32 v254, s0, 56
	s_add_u32 s4, s71, 0xe2800
	s_addc_u32 s5, s94, 0
	v_writelane_b32 v254, s1, 57
	v_writelane_b32 v254, s4, 58
	s_mov_b32 m0, s39
	v_lshl_add_u64 v[4:5], s[0:1], 0, v[180:181]
	v_writelane_b32 v254, s5, 59
	s_add_u32 s14, s4, 0x70000
	s_addc_u32 s15, s5, 0
	global_load_lds_dwordx4 v180, s[0:1]
	v_lshl_add_u64 v[4:5], v[4:5], 0, s[96:97]
	s_mov_b32 m0, s18
	v_lshlrev_b32_e32 v128, 2, v10
	global_load_lds_dwordx4 v[4:5], off
	s_mov_b32 m0, s40
	v_bfe_u32 v4, v8, 2, 2
	global_load_lds_dwordx4 v132, s[4:5]
	s_mov_b32 m0, s41
	v_lshlrev_b32_e32 v6, 3, v8
	global_load_lds_dwordx4 v132, s[14:15]
	v_or_b32_e32 v4, v128, v4
	v_and_b32_e32 v6, 24, v6
	v_lshlrev_b32_e32 v5, 5, v4
	v_lshl_or_b32 v4, v4, 8, v6
	v_add_u32_e32 v143, 0x4000, v4
	v_bitop3_b32 v4, v10, v8, 7 bitop3:0x78
	v_lshlrev_b32_e32 v145, 4, v4
	v_add_u32_e32 v4, 4, v10
	v_bitop3_b32 v4, v4, v8, 7 bitop3:0x78
	v_mov_b32_e32 v6, v181
	v_mov_b32_e32 v7, v181
	v_lshlrev_b32_e32 v144, 7, v9
	v_and_b32_e32 v142, 0xe0, v5
	v_lshlrev_b32_e32 v146, 4, v4
	v_bitop3_b32 v141, v5, 32, v186 bitop3:0x6c
	v_bitop3_b32 v140, v5, 64, v186 bitop3:0x6c
	v_bitop3_b32 v139, v5, s73, v186 bitop3:0x6c
	v_bitop3_b32 v138, v5, s74, v186 bitop3:0x6c
	v_bitop3_b32 v137, v5, s75, v186 bitop3:0x6c
	v_bitop3_b32 v136, v5, s79, v186 bitop3:0x6c
	v_bitop3_b32 v129, v5, s67, v5 bitop3:0xc
	v_mov_b32_e32 v4, v181
	v_mov_b32_e32 v5, v181
	v_mov_b64_e32 v[14:15], v[6:7]
	v_mov_b64_e32 v[22:23], v[6:7]
	v_mov_b64_e32 v[30:31], v[6:7]
	v_mov_b64_e32 v[38:39], v[6:7]
	v_mov_b64_e32 v[46:47], v[6:7]
	v_mov_b64_e32 v[54:55], v[6:7]
	v_mov_b64_e32 v[58:59], v[6:7]
	v_mov_b64_e32 v[10:11], v[6:7]
	v_mov_b64_e32 v[18:19], v[6:7]
	v_mov_b64_e32 v[26:27], v[6:7]
	v_mov_b64_e32 v[34:35], v[6:7]
	v_mov_b64_e32 v[42:43], v[6:7]
	v_mov_b64_e32 v[50:51], v[6:7]
	v_mov_b64_e32 v[62:63], v[6:7]
	v_mov_b64_e32 v[66:67], v[6:7]
	v_ashrrev_i32_e32 v125, 31, v124
	s_mov_b32 s17, 0
	v_mov_b32_e32 v133, v181
	v_mov_b32_e32 v130, v181
	v_mov_b32_e32 v131, v181
	s_mov_b64 s[4:5], s[76:77]
	v_mov_b64_e32 v[12:13], v[4:5]
	v_mov_b64_e32 v[20:21], v[4:5]
	v_mov_b64_e32 v[28:29], v[4:5]
	v_mov_b64_e32 v[36:37], v[4:5]
	v_mov_b64_e32 v[44:45], v[4:5]
	v_mov_b64_e32 v[52:53], v[4:5]
	v_mov_b64_e32 v[56:57], v[4:5]
	v_mov_b64_e32 v[8:9], v[4:5]
	v_mov_b64_e32 v[16:17], v[4:5]
	v_mov_b64_e32 v[24:25], v[4:5]
	v_mov_b64_e32 v[32:33], v[4:5]
	v_mov_b64_e32 v[40:41], v[4:5]
	v_mov_b64_e32 v[48:49], v[4:5]
	v_mov_b64_e32 v[60:61], v[4:5]
	s_mov_b32 s15, 0
	v_mov_b64_e32 v[64:65], v[4:5]
	s_waitcnt vmcnt(4) lgkmcnt(0)
	s_barrier
	s_mov_b64 s[4:5], s[76:77]
	s_mov_b32 s15, 0
	s_and_b32 s0, s15, 3
	s_lshl_b32 s0, s0, 15
	s_add_i32 s1, s15, 3
	s_and_b32 s1, s1, 3
	s_lshl_b32 s1, s1, 15
	s_add_i32 s16, s15, 2
	s_and_b32 s16, s16, 3
	s_lshl_b32 s16, s16, 15
	s_add_i32 s16, s16, s90
	v_add_u32_e32 v119, s0, v144
	v_add_u32_e32 v116, v119, v145
	v_add_u32_e32 v117, v119, v146
	ds_read_b128 v[84:87], v116
	ds_read_b128 v[88:91], v116 offset:2048
	ds_read_b128 v[92:95], v117
	ds_read_b128 v[96:99], v117 offset:2048
	ds_read_b128 v[100:103], v116 offset:4096
	ds_read_b128 v[104:107], v116 offset:6144
	ds_read_b128 v[108:111], v117 offset:4096
	ds_read_b128 v[112:115], v117 offset:6144
	s_cmp_ge_u32 s15, s70
	s_cbranch_scc1 .Ldx_nd0
	s_mov_b32 m0, s16
	s_add_u32 s18, s4, 0xfffff800
	s_addc_u32 s19, s5, -1
	global_load_lds_dwordx4 v180, s[18:19]
	s_add_i32 m0, s16, 0x2000
	s_add_u32 s22, s18, 0x80
	s_addc_u32 s23, s19, 0
	global_load_lds_dwordx4 v180, s[22:23]
	s_add_i32 m0, s16, 0x4000
	s_add_u32 s24, s4, 0x70000
	s_addc_u32 s25, s5, 0
	global_load_lds_dwordx4 v132, s[4:5]
	s_add_i32 m0, s16, 0x6000
	s_add_u32 s4, s4, 0xe0000
	s_addc_u32 s5, s5, 0
	global_load_lds_dwordx4 v132, s[24:25]

; #define LAS __attribute__((address_space(3)))
; #define ATT_KREAD(dst, c) do { _Pragma("unroll") for (int kb = 0; kb < 4; ++kb) _Pragma("unroll") for (int ds = 0; ds < 2; ++ds) \
;                 dst[kb * 2 + ds] = *(const LAS bf16x8*)(bp + (c) * 8192 + kb * 2048 + kfo + (((unsigned)(4 * ds + quad) ^ ksw) * 16)); } while (0)
; #define ATT_VWAIT15(lo_, hi_) asm volatile("s_waitcnt lgkmcnt(15)" : "+v"(lo_[0]), "+v"(lo_[1]), "+v"(lo_[2]), "+v"(lo_[3]), "+v"(lo_[4]), "+v"(lo_[5]), "+v"(lo_[6]), "+v"(lo_[7]), \
;                 "+v"(hi_[0]), "+v"(hi_[1]), "+v"(hi_[2]), "+v"(hi_[3]), "+v"(hi_[4]), "+v"(hi_[5]), "+v"(hi_[6]), "+v"(hi_[7]))
; #define ATT_SB __builtin_amdgcn_sched_barrier(0)
; template <bool DIFF>
; __device__ __forceinline__ void attn_item(LAS unsigned char* lds, const bf16_t* Z, bf16_t* MIX, int b, int h, int t, float lam, float shift, const float* gain, int tid, int wid, int lane) {
;     ...
;     for (int kt = 0; kt < nkt; ++kt) {
;         const int bnx = (bcur == 2) ? 0 : bcur + 1, bn2 = (bnx == 2) ? 0 : bnx + 1;
;         const bool more2 = (kt + 2 < nkt);
;         if (more2) ATT_DMA(kt + 2, bn2);
;         if (kt <= cq) {
;             LAS unsigned char* bp = lds + bcur * ATT_RING;
;             const float msk = 0.f;
;             const float sinit = DIFF ? (msk - shift) : 0.f;
;             bf16x8 kfA[8], kfB[8]; s16x4 vAl[8], vAh[8], vBl[8], vBh[8];
;             f32x4 s0[4], s1[4];
;             bf16x8 P[NC][2];
;             const unsigned bpa = (unsigned)(size_t)bp;
;     ...
;             ATT_KREAD(kfA, 0); ATT_SB;
;             if (DIFF) { ATT_KREAD(kfB, NC - 1); ATT_SMMA(s0, kfA, 0); ATT_SB;
;                         ATT_VISSUE(vAl, vAh, 0); ATT_SMMA(s1, kfB, NC - 1); ATT_SOFT(s0, 0); ATT_SB;
;                         ATT_SOFT(s1, NC - 1); ATT_PVW(0, vAl, vAh, 0); ATT_SB;
;                         ATT_VISSUE(vBl, vBh, 4); ATT_PV(NC - 1, vAl, vAh, 0); ATT_SB;
;                         ATT_PVW(0, vBl, vBh, 4); ATT_PV(NC - 1, vBl, vBh, 4); ATT_SB; }
;             else      { ATT_VISSUE(vAl, vAh, 0); ATT_SMMA(s0, kfA, 0); ATT_SB;
;                         ATT_VISSUE(vBl, vBh, 4); ATT_SOFT(s0, 0); ATT_SB;
;                         ATT_VWAIT15(vAl, vAh); ATT_PV(0, vAl, vAh, 0); ATT_PVW(0, vBl, vBh, 4); ATT_SB; }
.Ldx_loop:
	s_and_b32 s0, s15, 3
	s_lshl_b32 s0, s0, 15
	s_add_i32 s1, s15, 3
	s_and_b32 s1, s1, 3
	s_lshl_b32 s1, s1, 15
	s_add_i32 s16, s15, 2
	s_and_b32 s16, s16, 3
	s_lshl_b32 s16, s16, 15
	s_add_i32 s16, s16, s90
	s_cmp_gt_u32 s15, s83
	s_cbranch_scc1 .Ldx_pvo
	s_waitcnt lgkmcnt(0)
	v_add_u32_e32 v119, s0, v144
	v_add_u32_e32 v116, v119, v145
	v_add_u32_e32 v117, v119, v146
	ds_read_b128 v[84:87], v116
	ds_read_b128 v[88:91], v116 offset:2048
	ds_read_b128 v[92:95], v117
	ds_read_b128 v[96:99], v117 offset:2048
	ds_read_b128 v[100:103], v116 offset:4096
	ds_read_b128 v[104:107], v116 offset:6144
	ds_read_b128 v[108:111], v117 offset:4096
	ds_read_b128 v[112:115], v117 offset:6144
	v_add_u32_e32 v118, s1, v143
	v_add_u32_e32 v120, v118, v138
	v_add_u32_e32 v121, v118, v137
	v_add_u32_e32 v122, v118, v136
	v_add_u32_e32 v123, v118, v129
	v_mfma_f32_16x16x32_bf16 v[64:67], v[148:151], v[220:223], v[64:67]
	v_add_f32_e32 v131, v131, v188
	v_add_f32_e32 v131, v131, v189
	v_mfma_f32_16x16x32_bf16 v[60:63], v[156:159], v[220:223], v[60:63]
	v_add_f32_e32 v131, v131, v190
	v_add_f32_e32 v131, v131, v191
	v_mfma_f32_16x16x32_bf16 v[56:59], v[148:151], v[228:231], v[56:59]
	v_add_f32_e32 v131, v131, v192
	v_add_f32_e32 v131, v131, v193
	v_mfma_f32_16x16x32_bf16 v[52:55], v[156:159], v[228:231], v[52:55]
	v_add_f32_e32 v131, v131, v194
	v_add_f32_e32 v131, v131, v195
	v_mfma_f32_16x16x32_bf16 v[64:67], v[152:155], v[224:227], v[64:67]
	v_add_f32_e32 v131, v131, v196
	v_add_f32_e32 v131, v131, v197
	v_mfma_f32_16x16x32_bf16 v[60:63], v[160:163], v[224:227], v[60:63]
	v_add_f32_e32 v131, v131, v198
	v_add_f32_e32 v131, v131, v199
	v_mfma_f32_16x16x32_bf16 v[56:59], v[152:155], v[232:235], v[56:59]
	v_add_f32_e32 v131, v131, v200
	v_add_f32_e32 v131, v131, v201
	v_mfma_f32_16x16x32_bf16 v[52:55], v[160:163], v[232:235], v[52:55]
	v_add_f32_e32 v131, v131, v202
	v_add_f32_e32 v131, v131, v203
	ds_read_b64_tr_b16 v[148:149], v120
	ds_read_b64_tr_b16 v[150:151], v120 offset:4096
	ds_read_b64_tr_b16 v[152:153], v120 offset:8192
	ds_read_b64_tr_b16 v[154:155], v120 offset:12288
	ds_read_b64_tr_b16 v[156:157], v121
	ds_read_b64_tr_b16 v[158:159], v121 offset:4096
	ds_read_b64_tr_b16 v[160:161], v121 offset:8192
	ds_read_b64_tr_b16 v[162:163], v121 offset:12288
	v_mfma_f32_16x16x32_bf16 v[48:51], v[164:167], v[220:223], v[48:51]
	v_add_f32_e32 v130, v130, v204
	v_add_f32_e32 v130, v130, v205
	v_mfma_f32_16x16x32_bf16 v[40:43], v[172:175], v[220:223], v[40:43]
	v_add_f32_e32 v130, v130, v206
	v_add_f32_e32 v130, v130, v207
	v_mfma_f32_16x16x32_bf16 v[44:47], v[164:167], v[228:231], v[44:47]
	v_add_f32_e32 v130, v130, v208
	v_add_f32_e32 v130, v130, v209
	v_mfma_f32_16x16x32_bf16 v[36:39], v[172:175], v[228:231], v[36:39]
	v_add_f32_e32 v130, v130, v210
	v_add_f32_e32 v130, v130, v211
	v_mfma_f32_16x16x32_bf16 v[48:51], v[168:171], v[224:227], v[48:51]
	v_add_f32_e32 v130, v130, v212
	v_add_f32_e32 v130, v130, v213
	v_mfma_f32_16x16x32_bf16 v[40:43], v[176:179], v[224:227], v[40:43]
	v_add_f32_e32 v130, v130, v214
	v_add_f32_e32 v130, v130, v215
	v_mfma_f32_16x16x32_bf16 v[44:47], v[168:171], v[232:235], v[44:47]
	v_add_f32_e32 v130, v130, v216
	v_add_f32_e32 v130, v130, v217
	v_mfma_f32_16x16x32_bf16 v[36:39], v[176:179], v[232:235], v[36:39]
	v_add_f32_e32 v130, v130, v218
	v_add_f32_e32 v130, v130, v219
	ds_read_b64_tr_b16 v[164:165], v122
	ds_read_b64_tr_b16 v[166:167], v122 offset:4096
	ds_read_b64_tr_b16 v[168:169], v122 offset:8192
	ds_read_b64_tr_b16 v[170:171], v122 offset:12288
	ds_read_b64_tr_b16 v[172:173], v123
	ds_read_b64_tr_b16 v[174:175], v123 offset:4096
	ds_read_b64_tr_b16 v[176:177], v123 offset:8192
	ds_read_b64_tr_b16 v[178:179], v123 offset:12288
	s_cmp_ge_u32 s15, s70
	s_cbranch_scc1 .Ldx_nd
	s_mov_b32 m0, s16
	s_add_u32 s18, s4, 0xfffff800
	s_addc_u32 s19, s5, -1
	global_load_lds_dwordx4 v180, s[18:19]
	s_add_i32 m0, s16, 0x2000
	s_add_u32 s22, s18, 0x80
	s_addc_u32 s23, s19, 0
	global_load_lds_dwordx4 v180, s[22:23]
	s_add_i32 m0, s16, 0x4000
	s_add_u32 s24, s4, 0x70000
	s_addc_u32 s25, s5, 0
	global_load_lds_dwordx4 v132, s[4:5]
	s_add_i32 m0, s16, 0x6000
	s_add_u32 s4, s4, 0xe0000
	s_addc_u32 s5, s5, 0
	global_load_lds_dwordx4 v132, s[24:25]

; template <bool DIFF>
; __device__ __forceinline__ void attn_item(LAS unsigned char* lds, const bf16_t* Z, bf16_t* MIX, int b, int h, int t, float lam, float shift, const float* gain, int tid, int wid, int lane) {
;     ...
;     float inv0 = 1.f, inv1 = 0.f;
;     if (DIFF) {
; #pragma unroll
;         for (int c = 0; c < NC; ++c) l[c] = quad_sum(l[c]);
;         inv0 = 1.0f / l[0]; inv1 = lam / l[NC - 1];
;     }
;     float ss = 0.f;
; #pragma unroll
;     for (int eb = 0; eb < 8; ++eb)
; #pragma unroll
;         for (int i = 0; i < 4; ++i) { float v = O[0][eb][i] * inv0; if (DIFF) v -= O[NC - 1][eb][i] * inv1; O[0][eb][i] = v; ss += v * v; }
;     ss = quad_sum(ss);
;     const float r = rsqrtf(ss * (1.0f / 128.0f) + EPS) * (DIFF ? 0.8f : 1.0f);
;     const int row = row0 + q16;
;     const bf16_t* gp = Z + (size_t)row * DIN + gcol + 4 * quad;
;     bf16_t* op = MIX + (size_t)row * DM + (DIFF ? 1024 : 0) + 128 * h + 4 * quad;
; #pragma unroll
;     for (int eb = 0; eb < 8; ++eb) {
;         const u32x2 gw = *(const u32x2*)(gp + 16 * eb);
;         const f32x4 gn = *(const f32x4*)(gain + 16 * eb + 4 * quad);
.Ldx_done:
.LBB0_574:
	s_waitcnt lgkmcnt(0)
	ds_swizzle_b32 v68, v131 offset:swizzle(SWAP,16)
	ds_swizzle_b32 v69, v130 offset:swizzle(SWAP,16)
	v_ashrrev_i32_e32 v129, 31, v128
	v_lshlrev_b64 v[80:81], 1, v[128:129]
	s_lshl_b32 s86, s80, 1
	s_waitcnt lgkmcnt(0)
	v_add_f32_e32 v68, v131, v68
	v_mov_b32_e32 v70, v68
	s_nop 1
	v_permlane32_swap_b32_e32 v68, v70
	v_add_f32_e32 v68, v68, v70
	v_div_scale_f32 v70, s[0:1], v68, v68, 1.0
	v_rcp_f32_e32 v72, v70
	v_add_f32_e32 v69, v130, v69
	v_mov_b32_e32 v71, v69
	s_nop 1
	v_permlane32_swap_b32_e32 v69, v71
	v_add_f32_e32 v69, v69, v71
	v_fma_f32 v71, -v70, v72, 1.0
	v_fmac_f32_e32 v72, v71, v72
	v_div_scale_f32 v71, vcc, 1.0, v68, 1.0
	v_mul_f32_e32 v73, v71, v72
	v_fma_f32 v74, -v70, v73, v71
	v_fmac_f32_e32 v73, v74, v72
	v_fma_f32 v70, -v70, v73, v71
	v_div_scale_f32 v71, s[0:1], v69, v69, s28
	v_rcp_f32_e32 v74, v71
	v_div_fmas_f32 v70, v70, v72, v73
	v_div_fixup_f32 v76, v70, v68, 1.0
	s_movk_i32 s0, 0x3000
	v_fma_f32 v68, -v71, v74, 1.0
	v_fmac_f32_e32 v74, v68, v74
	v_div_scale_f32 v68, vcc, s28, v69, s28
	v_mul_f32_e32 v70, v68, v74
	v_fma_f32 v72, -v71, v70, v68
	v_fmac_f32_e32 v70, v72, v74
	v_fma_f32 v68, -v71, v70, v68
	v_lshl_add_u64 v[72:73], v[126:127], 0, v[80:81]
	v_div_fmas_f32 v68, v68, v74, v70
	v_lshl_add_u64 v[70:71], v[72:73], 0, s[92:93]
	v_add_co_u32_e32 v72, vcc, s0, v72
	v_div_fixup_f32 v78, v68, v69, s28
	v_lshlrev_b64 v[68:69], 12, v[124:125]
	v_addc_co_u32_e32 v73, vcc, 0, v73, vcc
	v_lshl_add_u64 v[82:83], s[88:89], 0, v[68:69]
	v_lshl_add_u64 v[68:69], v[128:129], 2, s[84:85]
	v_mbcnt_lo_u32_b32 v150, -1, 0
	v_mbcnt_hi_u32_b32 v150, -1, v150
	v_and_b32_e32 v150, 16, v150
	v_lshrrev_b32_e32 v151, 1, v150
	v_add_u32_e32 v150, v150, v151
	v_mov_b32_e32 v151, 0
	v_lshl_add_u64 v[152:153], v[70:71], 0, v[150:151]
	global_load_dwordx4 v[84:87], v[68:69], off
	global_load_dwordx4 v[116:119], v[152:153], off
	global_load_dwordx4 v[88:91], v[68:69], off offset:64
	global_load_dwordx4 v[92:95], v[68:69], off offset:128
	global_load_dwordx4 v[120:123], v[152:153], off offset:64
	global_load_dwordx4 v[96:99], v[68:69], off offset:192
	global_load_dwordx4 v[100:103], v[68:69], off offset:256
	global_load_dwordx4 v[132:135], v[152:153], off offset:128
	global_load_dwordx4 v[104:107], v[68:69], off offset:320
	global_load_dwordx4 v[108:111], v[68:69], off offset:384
	global_load_dwordx4 v[136:139], v[152:153], off offset:192
	global_load_dwordx4 v[112:115], v[68:69], off offset:448
	v_pk_mul_f32 v[56:57], v[56:57], v[78:79] op_sel_hi:[1,0]
	v_pk_mul_f32 v[58:59], v[58:59], v[78:79] op_sel_hi:[1,0]
	v_pk_fma_f32 v[56:57], v[64:65], v[76:77], v[56:57] op_sel_hi:[1,0,1] neg_lo:[0,0,1] neg_hi:[0,0,1]
	v_pk_fma_f32 v[58:59], v[66:67], v[76:77], v[58:59] op_sel_hi:[1,0,1] neg_lo:[0,0,1] neg_hi:[0,0,1]
	v_pk_mul_f32 v[64:65], v[56:57], v[56:57]
	v_pk_mul_f32 v[66:67], v[58:59], v[58:59]
	v_pk_mul_f32 v[52:53], v[52:53], v[78:79] op_sel_hi:[1,0]
	v_add_f32_e32 v64, v64, v65
	v_pk_fma_f32 v[52:53], v[60:61], v[76:77], v[52:53] op_sel_hi:[1,0,1] neg_lo:[0,0,1] neg_hi:[0,0,1]
	v_add_f32_e32 v64, v66, v64
	v_pk_mul_f32 v[54:55], v[54:55], v[78:79] op_sel_hi:[1,0]
	v_pk_mul_f32 v[60:61], v[52:53], v[52:53]
	v_add_f32_e32 v64, v67, v64
	v_pk_fma_f32 v[54:55], v[62:63], v[76:77], v[54:55] op_sel_hi:[1,0,1] neg_lo:[0,0,1] neg_hi:[0,0,1]
	v_add_f32_e32 v60, v60, v64
	v_pk_mul_f32 v[62:63], v[54:55], v[54:55]
	v_pk_mul_f32 v[44:45], v[44:45], v[78:79] op_sel_hi:[1,0]
	v_add_f32_e32 v60, v61, v60
	v_pk_fma_f32 v[44:45], v[48:49], v[76:77], v[44:45] op_sel_hi:[1,0,1] neg_lo:[0,0,1] neg_hi:[0,0,1]
	v_add_f32_e32 v60, v62, v60
	v_pk_mul_f32 v[46:47], v[46:47], v[78:79] op_sel_hi:[1,0]
	v_pk_mul_f32 v[48:49], v[44:45], v[44:45]
	v_add_f32_e32 v60, v63, v60
	v_pk_fma_f32 v[46:47], v[50:51], v[76:77], v[46:47] op_sel_hi:[1,0,1] neg_lo:[0,0,1] neg_hi:[0,0,1]
	v_add_f32_e32 v48, v48, v60
	v_pk_mul_f32 v[50:51], v[46:47], v[46:47]
	v_pk_mul_f32 v[36:37], v[36:37], v[78:79] op_sel_hi:[1,0]
	v_add_f32_e32 v48, v49, v48
	v_pk_fma_f32 v[36:37], v[40:41], v[76:77], v[36:37] op_sel_hi:[1,0,1] neg_lo:[0,0,1] neg_hi:[0,0,1]
	v_add_f32_e32 v48, v50, v48
	v_pk_mul_f32 v[38:39], v[38:39], v[78:79] op_sel_hi:[1,0]
	v_pk_mul_f32 v[40:41], v[36:37], v[36:37]
	v_add_f32_e32 v48, v51, v48
	v_pk_fma_f32 v[38:39], v[42:43], v[76:77], v[38:39] op_sel_hi:[1,0,1] neg_lo:[0,0,1] neg_hi:[0,0,1]
	v_add_f32_e32 v40, v40, v48
	v_pk_mul_f32 v[42:43], v[38:39], v[38:39]
	v_pk_mul_f32 v[28:29], v[28:29], v[78:79] op_sel_hi:[1,0]
	v_add_f32_e32 v40, v41, v40
	v_pk_fma_f32 v[28:29], v[32:33], v[76:77], v[28:29] op_sel_hi:[1,0,1] neg_lo:[0,0,1] neg_hi:[0,0,1]
	v_add_f32_e32 v40, v42, v40
	v_pk_mul_f32 v[30:31], v[30:31], v[78:79] op_sel_hi:[1,0]
	v_pk_mul_f32 v[32:33], v[28:29], v[28:29]
	v_add_f32_e32 v40, v43, v40
	v_pk_fma_f32 v[30:31], v[34:35], v[76:77], v[30:31] op_sel_hi:[1,0,1] neg_lo:[0,0,1] neg_hi:[0,0,1]
	v_add_f32_e32 v32, v32, v40
	v_pk_mul_f32 v[34:35], v[30:31], v[30:31]
	v_pk_mul_f32 v[20:21], v[20:21], v[78:79] op_sel_hi:[1,0]
	v_add_f32_e32 v32, v33, v32
	v_pk_fma_f32 v[20:21], v[24:25], v[76:77], v[20:21] op_sel_hi:[1,0,1] neg_lo:[0,0,1] neg_hi:[0,0,1]
	v_add_f32_e32 v32, v34, v32
	v_pk_mul_f32 v[22:23], v[22:23], v[78:79] op_sel_hi:[1,0]
	v_pk_mul_f32 v[24:25], v[20:21], v[20:21]
	v_add_f32_e32 v32, v35, v32
	v_pk_fma_f32 v[22:23], v[26:27], v[76:77], v[22:23] op_sel_hi:[1,0,1] neg_lo:[0,0,1] neg_hi:[0,0,1]
	v_add_f32_e32 v24, v24, v32
	v_pk_mul_f32 v[26:27], v[22:23], v[22:23]
	v_pk_mul_f32 v[12:13], v[12:13], v[78:79] op_sel_hi:[1,0]
	v_add_f32_e32 v24, v25, v24
	v_pk_fma_f32 v[12:13], v[16:17], v[76:77], v[12:13] op_sel_hi:[1,0,1] neg_lo:[0,0,1] neg_hi:[0,0,1]
	v_add_f32_e32 v24, v26, v24
	v_pk_mul_f32 v[14:15], v[14:15], v[78:79] op_sel_hi:[1,0]
	v_pk_mul_f32 v[16:17], v[12:13], v[12:13]
	v_add_f32_e32 v24, v27, v24
	v_pk_fma_f32 v[14:15], v[18:19], v[76:77], v[14:15] op_sel_hi:[1,0,1] neg_lo:[0,0,1] neg_hi:[0,0,1]
	v_add_f32_e32 v16, v16, v24
	v_pk_mul_f32 v[18:19], v[14:15], v[14:15]
	v_pk_mul_f32 v[4:5], v[4:5], v[78:79] op_sel_hi:[1,0]
	v_add_f32_e32 v16, v17, v16
	v_pk_fma_f32 v[8:9], v[8:9], v[76:77], v[4:5] op_sel_hi:[1,0,1] neg_lo:[0,0,1] neg_hi:[0,0,1]
	v_add_f32_e32 v16, v18, v16
	v_pk_mul_f32 v[6:7], v[6:7], v[78:79] op_sel_hi:[1,0]
	v_pk_mul_f32 v[4:5], v[8:9], v[8:9]
	v_add_f32_e32 v16, v19, v16
	v_pk_fma_f32 v[10:11], v[10:11], v[76:77], v[6:7] op_sel_hi:[1,0,1] neg_lo:[0,0,1] neg_hi:[0,0,1]
	v_add_f32_e32 v4, v4, v16
	v_pk_mul_f32 v[6:7], v[10:11], v[10:11]
	v_add_f32_e32 v4, v5, v4
	v_add_f32_e32 v4, v6, v4
	v_add_f32_e32 v6, v7, v4
	ds_swizzle_b32 v7, v6 offset:swizzle(SWAP,16)
	v_mov_b32_e32 v18, 0x358637bd
	s_mov_b32 s87, s27
	v_lshl_add_u64 v[4:5], v[82:83], 0, s[86:87]
	v_lshl_add_u64 v[16:17], v[4:5], 0, v[80:81]
	s_waitcnt lgkmcnt(0)
; __device__ __forceinline__ unsigned cvtpk(float lo, float hi) { f32x2 v = {lo, hi}; bf16x2_t b = __builtin_convertvector(v, bf16x2_t); return __builtin_bit_cast(unsigned, b); }
; __device__ __forceinline__ float bflo(unsigned u) { return __uint_as_float(u << 16); }
; __device__ __forceinline__ float bfhi(unsigned u) { return __uint_as_float(u & 0xffff0000u); }
; template <bool DIFF>
; __device__ __forceinline__ void attn_item(LAS unsigned char* lds, const bf16_t* Z, bf16_t* MIX, int b, int h, int t, float lam, float shift, const float* gain, int tid, int wid, int lane) {
;     ...
;     ss = quad_sum(ss);
;     const float r = rsqrtf(ss * (1.0f / 128.0f) + EPS) * (DIFF ? 0.8f : 1.0f);
;     const int row = row0 + q16;
;     const bf16_t* gp = Z + (size_t)row * DIN + gcol + 4 * quad;
;     bf16_t* op = MIX + (size_t)row * DM + (DIFF ? 1024 : 0) + 128 * h + 4 * quad;
; #pragma unroll
;     for (int eb = 0; eb < 8; ++eb) {
;         const u32x2 gw = *(const u32x2*)(gp + 16 * eb);
;         const f32x4 gn = *(const f32x4*)(gain + 16 * eb + 4 * quad);
;         u32x2 w; w.x = cvtpk(O[0][eb][0] * r * gn.x * bflo(gw.x), O[0][eb][1] * r * gn.y * bfhi(gw.x));
;         w.y = cvtpk(O[0][eb][2] * r * gn.z * bflo(gw.y), O[0][eb][3] * r * gn.w * bfhi(gw.y));
;         *(u32x2*)(op + 16 * eb) = w;
;     }
	v_add_f32_e32 v6, v6, v7
	v_mov_b32_e32 v7, v6
	s_nop 1
	v_permlane32_swap_b32_e32 v6, v7
	v_add_f32_e32 v6, v6, v7
	v_fmamk_f32 v6, v6, 0x3c000000, v18
	v_mul_f32_e32 v7, 0x4b800000, v6
	v_cmp_gt_f32_e32 vcc, s42, v6
	s_nop 1
	v_cndmask_b32_e32 v6, v6, v7, vcc
	v_rsq_f32_e32 v24, v6
	s_nop 0
	v_mul_f32_e32 v25, 0x45800000, v24
	v_cndmask_b32_e32 v24, v24, v25, vcc
	v_mul_f32_e32 v24, 0x3f4ccccd, v24
	v_pk_mul_f32 v[56:57], v[56:57], v[24:25] op_sel_hi:[1,0]
	v_pk_mul_f32 v[58:59], v[58:59], v[24:25] op_sel_hi:[1,0]
	v_pk_mul_f32 v[52:53], v[52:53], v[24:25] op_sel_hi:[1,0]
	v_pk_mul_f32 v[54:55], v[54:55], v[24:25] op_sel_hi:[1,0]
	v_pk_mul_f32 v[44:45], v[44:45], v[24:25] op_sel_hi:[1,0]
	v_pk_mul_f32 v[46:47], v[46:47], v[24:25] op_sel_hi:[1,0]
	v_pk_mul_f32 v[36:37], v[36:37], v[24:25] op_sel_hi:[1,0]
	v_pk_mul_f32 v[38:39], v[38:39], v[24:25] op_sel_hi:[1,0]
	v_pk_mul_f32 v[28:29], v[28:29], v[24:25] op_sel_hi:[1,0]
	v_pk_mul_f32 v[30:31], v[30:31], v[24:25] op_sel_hi:[1,0]
	v_pk_mul_f32 v[20:21], v[20:21], v[24:25] op_sel_hi:[1,0]
	v_pk_mul_f32 v[22:23], v[22:23], v[24:25] op_sel_hi:[1,0]
	v_pk_mul_f32 v[12:13], v[12:13], v[24:25] op_sel_hi:[1,0]
	v_pk_mul_f32 v[14:15], v[14:15], v[24:25] op_sel_hi:[1,0]
	v_pk_mul_f32 v[8:9], v[8:9], v[24:25] op_sel_hi:[1,0]
	v_pk_mul_f32 v[10:11], v[10:11], v[24:25] op_sel_hi:[1,0]
	s_waitcnt vmcnt(0)
	v_permlane16_swap_b32_e32 v116, v118
	v_permlane16_swap_b32_e32 v117, v119
	v_permlane16_swap_b32_e32 v120, v122
	v_permlane16_swap_b32_e32 v121, v123
	v_permlane16_swap_b32_e32 v132, v134
	v_permlane16_swap_b32_e32 v133, v135
	v_permlane16_swap_b32_e32 v136, v138
	v_permlane16_swap_b32_e32 v137, v139
	v_mbcnt_lo_u32_b32 v150, -1, 0
	v_mbcnt_hi_u32_b32 v150, -1, v150
	v_and_b32_e32 v150, 16, v150
	v_lshrrev_b32_e32 v151, 1, v150
	v_add_u32_e32 v150, v150, v151
	v_mov_b32_e32 v151, 0
	v_lshl_add_u64 v[148:149], v[16:17], 0, v[150:151]
	v_lshlrev_b32_e32 v60, 16, v116
	v_and_b32_e32 v61, 0xffff0000, v116
	v_lshlrev_b32_e32 v62, 16, v117
	v_and_b32_e32 v63, 0xffff0000, v117
	v_pk_mul_f32 v[56:57], v[84:85], v[56:57]
	v_pk_mul_f32 v[58:59], v[86:87], v[58:59]
	v_pk_mul_f32 v[56:57], v[56:57], v[60:61]
	v_pk_mul_f32 v[58:59], v[58:59], v[62:63]
	v_cvt_pk_bf16_f32 v56, v56, v57
	v_cvt_pk_bf16_f32 v57, v58, v59
	v_lshlrev_b32_e32 v40, 16, v118
	v_and_b32_e32 v41, 0xffff0000, v118
	v_lshlrev_b32_e32 v42, 16, v119
	v_and_b32_e32 v43, 0xffff0000, v119
	v_pk_mul_f32 v[52:53], v[88:89], v[52:53]
	v_pk_mul_f32 v[54:55], v[90:91], v[54:55]
	v_pk_mul_f32 v[52:53], v[52:53], v[40:41]
	v_pk_mul_f32 v[54:55], v[54:55], v[42:43]
	v_cvt_pk_bf16_f32 v58, v52, v53
	v_cvt_pk_bf16_f32 v59, v54, v55
	s_nop 1
	v_permlane16_swap_b32_e32 v56, v58
	v_permlane16_swap_b32_e32 v57, v59
	global_store_dwordx4 v[148:149], v[56:59], off offset:2048
	v_lshlrev_b32_e32 v60, 16, v120
	v_and_b32_e32 v61, 0xffff0000, v120
	v_lshlrev_b32_e32 v62, 16, v121
	v_and_b32_e32 v63, 0xffff0000, v121
	v_pk_mul_f32 v[44:45], v[92:93], v[44:45]
	v_pk_mul_f32 v[46:47], v[94:95], v[46:47]
	v_pk_mul_f32 v[44:45], v[44:45], v[60:61]
	v_pk_mul_f32 v[46:47], v[46:47], v[62:63]
	v_cvt_pk_bf16_f32 v44, v44, v45
	v_cvt_pk_bf16_f32 v45, v46, v47
	v_lshlrev_b32_e32 v40, 16, v122
	v_and_b32_e32 v41, 0xffff0000, v122
	v_lshlrev_b32_e32 v42, 16, v123
	v_and_b32_e32 v43, 0xffff0000, v123
	v_pk_mul_f32 v[36:37], v[96:97], v[36:37]
	v_pk_mul_f32 v[38:39], v[98:99], v[38:39]
	v_pk_mul_f32 v[36:37], v[36:37], v[40:41]
	v_pk_mul_f32 v[38:39], v[38:39], v[42:43]
	v_cvt_pk_bf16_f32 v46, v36, v37
	v_cvt_pk_bf16_f32 v47, v38, v39
	s_nop 1
	v_permlane16_swap_b32_e32 v44, v46
	v_permlane16_swap_b32_e32 v45, v47
	global_store_dwordx4 v[148:149], v[44:47], off offset:2112
	v_lshlrev_b32_e32 v60, 16, v132
	v_and_b32_e32 v61, 0xffff0000, v132
	v_lshlrev_b32_e32 v62, 16, v133
	v_and_b32_e32 v63, 0xffff0000, v133
	v_pk_mul_f32 v[28:29], v[100:101], v[28:29]
	v_pk_mul_f32 v[30:31], v[102:103], v[30:31]
	v_pk_mul_f32 v[28:29], v[28:29], v[60:61]
	v_pk_mul_f32 v[30:31], v[30:31], v[62:63]
	v_cvt_pk_bf16_f32 v28, v28, v29
	v_cvt_pk_bf16_f32 v29, v30, v31
	v_lshlrev_b32_e32 v40, 16, v134
	v_and_b32_e32 v41, 0xffff0000, v134
	v_lshlrev_b32_e32 v42, 16, v135
	v_and_b32_e32 v43, 0xffff0000, v135
	v_pk_mul_f32 v[20:21], v[104:105], v[20:21]
	v_pk_mul_f32 v[22:23], v[106:107], v[22:23]
	v_pk_mul_f32 v[20:21], v[20:21], v[40:41]
	v_pk_mul_f32 v[22:23], v[22:23], v[42:43]
	v_cvt_pk_bf16_f32 v30, v20, v21
	v_cvt_pk_bf16_f32 v31, v22, v23
	s_nop 1
	v_permlane16_swap_b32_e32 v28, v30
	v_permlane16_swap_b32_e32 v29, v31
	global_store_dwordx4 v[148:149], v[28:31], off offset:2176
	v_lshlrev_b32_e32 v60, 16, v136
	v_and_b32_e32 v61, 0xffff0000, v136
	v_lshlrev_b32_e32 v62, 16, v137
	v_and_b32_e32 v63, 0xffff0000, v137
	v_pk_mul_f32 v[12:13], v[108:109], v[12:13]
	v_pk_mul_f32 v[14:15], v[110:111], v[14:15]
	v_pk_mul_f32 v[12:13], v[12:13], v[60:61]
	v_pk_mul_f32 v[14:15], v[14:15], v[62:63]
	v_cvt_pk_bf16_f32 v12, v12, v13
	v_cvt_pk_bf16_f32 v13, v14, v15
	v_lshlrev_b32_e32 v40, 16, v138
	v_and_b32_e32 v41, 0xffff0000, v138
	v_lshlrev_b32_e32 v42, 16, v139
	v_and_b32_e32 v43, 0xffff0000, v139
	v_pk_mul_f32 v[8:9], v[112:113], v[8:9]
	v_pk_mul_f32 v[10:11], v[114:115], v[10:11]
	v_pk_mul_f32 v[8:9], v[8:9], v[40:41]
	v_pk_mul_f32 v[10:11], v[10:11], v[42:43]
	v_cvt_pk_bf16_f32 v14, v8, v9
	v_cvt_pk_bf16_f32 v15, v10, v11
	s_nop 1
	v_permlane16_swap_b32_e32 v12, v14
	v_permlane16_swap_b32_e32 v13, v15
	global_store_dwordx4 v[148:149], v[12:15], off offset:2240
	s_nop 1
	v_mov_b32_e32 v15, v183
	s_cmp_lg_u32 s98, 0
	s_cbranch_scc1 .Lp2_item_done
	s_cmp_lt_i32 s9, 3
	s_cbranch_scc1 .LBB0_579
	s_cmp_lt_i32 s9, 4
	s_cbranch_scc1 .LBB0_580
	s_cmp_lt_i32 s9, 5
	s_cbranch_scc1 .LBB0_581
	s_cmp_lg_u32 s9, 5
	s_cbranch_scc0 .LBB0_582
	s_cmp_eq_u32 s9, 6
	s_cselect_b64 vcc, -1, 0
	v_mov_b32_e32 v4, 0xba38b001
	v_mov_b32_e32 v5, 0xbab8b5c7
	v_cndmask_b32_e32 v12, v4, v5, vcc
	s_cbranch_execz .LBB0_583
	s_branch .LBB0_584
